# kprep phase: 4 rows in flight per wave, DPP reductions instead of ds_bpermute, rope values loaded once per wave
# speedup vs baseline: 1.0060x; 1.0060x over previous
; __device__ __forceinline__ unsigned pk2(float lo, float hi) { f32x2 v = {lo, hi}; bf16x2_t b = __builtin_convertvector(v, bf16x2_t); return __builtin_bit_cast(unsigned, b); }
; __device__ __forceinline__ float bf_lo(unsigned w) { return __uint_as_float(w << 16); }
; __device__ __forceinline__ float bf_hi(unsigned w) { return __uint_as_float(w & 0xffff0000u); }
; __device__ __forceinline__ void kprep_phase(const Args& a) {
;     const int tid = threadIdx.x, lane = tid & 63, w = tid >> 6; const int gw = blockIdx.x * 8 + w, NGW = gridDim.x * 8;
;     bf16_t* QKV = (bf16_t*)(a.ws + WS_QKV); const float* ROPE = (const float*)(a.ws + WS_ROPE); const float* kgain = a.in[11];
;     const int d4 = 4 * (lane & 15); const f32x4 g = *(const f32x4*)(kgain + d4); const bool lowhalf = (lane & 8) == 0; const int j = d4 & 31;
; #pragma unroll 2
;     for (int row = gw; row < MT_; row += NGW) {
;         u32x2* p = (u32x2*)(QKV + (size_t)row * NQKV + 1024 + 4 * lane);
;         const u32x2 v = *p; float f0 = bf_lo(v.x), f1 = bf_hi(v.x), f2 = bf_lo(v.y), f3 = bf_hi(v.y);
;         float ss = (f0 * f0 + f1 * f1) + (f2 * f2 + f3 * f3);
;         ss += __shfl_xor(ss, 1); ss += __shfl_xor(ss, 2); ss += __shfl_xor(ss, 4); ss += __shfl_xor(ss, 8);
;         const float rstd = rsqrtf(ss * (1.0f / 64.0f) + 1e-6f);
;         f0 *= rstd * g[0]; f1 *= rstd * g[1]; f2 *= rstd * g[2]; f3 *= rstd * g[3];
;         if (row < M_) {
;             const float p0 = __shfl_xor(f0, 8), p1 = __shfl_xor(f1, 8), p2 = __shfl_xor(f2, 8), p3 = __shfl_xor(f3, 8);
;             const float* rp = ROPE + (size_t)(row & (SEQ - 1)) * 64 + j; const f32x4 cs = *(const f32x4*)rp, sn = *(const f32x4*)(rp + 32);
;             if (lowhalf) { f0 = f0 * cs[0] - p0 * sn[0]; f1 = f1 * cs[1] - p1 * sn[1]; f2 = f2 * cs[2] - p2 * sn[2]; f3 = f3 * cs[3] - p3 * sn[3]; }
;             else         { f0 = p0 * sn[0] + f0 * cs[0]; f1 = p1 * sn[1] + f1 * cs[1]; f2 = p2 * sn[2] + f2 * cs[2]; f3 = p3 * sn[3] + f3 * cs[3]; }
;         }
;         u32x2 o; o.x = pk2(f0, f1); o.y = pk2(f2, f3); *p = o;
;     }
.LBB0_442:
	s_or_b64 exec, exec, s[12:13]
	v_add_u32_e32 v26, s20, v26
	s_waitcnt vmcnt(0)
	v_cvt_pk_bf16_f32 v4, v20, v21
	v_cvt_pk_bf16_f32 v5, v18, v19
	v_cmp_lt_i32_e64 s[0:1], s24, v26
	global_store_dwordx2 v[16:17], v[4:5], off
	v_add_u32_e32 v31, s21, v31
	s_or_b64 s[10:11], s[0:1], s[10:11]
	v_lshl_add_u64 v[16:17], v[16:17], 0, s[8:9]
	s_andn2_b64 exec, exec, s[10:11]
	s_cbranch_execz .LBB0_448
	s_branch .Lkp_orig
.LBB0_443:
	s_cmpk_lg_u32 s3, 0x100
	s_cbranch_scc1 .Lkp_orig
	v_mov_b32_e32 v34, 0
	v_bfrev_b32_e32 v33, 1
	v_cndmask_b32_e32 v33, v33, v34, vcc
	v_and_b32_e32 v4, 0x7ffc0, v31
	v_lshlrev_b32_e32 v12, 2, v4
	v_lshl_add_u64 v[4:5], v[14:15], 0, v[12:13]
	global_load_dwordx4 v[64:67], v[4:5], off
	global_load_dwordx4 v[68:71], v[4:5], off offset:128
	v_add_co_u32_e32 v4, vcc, 0x80000, v4
	s_nop 1
	v_addc_co_u32_e32 v5, vcc, 0, v5, vcc
	global_load_dwordx4 v[72:75], v[4:5], off
	global_load_dwordx4 v[76:79], v[4:5], off offset:128
	v_add_co_u32_e32 v4, vcc, 0x80000, v4
	s_nop 1
	v_addc_co_u32_e32 v5, vcc, 0, v5, vcc
	global_load_dwordx4 v[80:83], v[4:5], off
	global_load_dwordx4 v[84:87], v[4:5], off offset:128
	v_add_co_u32_e32 v4, vcc, 0x80000, v4
	s_nop 1
	v_addc_co_u32_e32 v5, vcc, 0, v5, vcc
	global_load_dwordx4 v[88:91], v[4:5], off
	global_load_dwordx4 v[92:95], v[4:5], off offset:128
	s_mov_b32 s0, 0
.Lkp_loop:
	v_mov_b64_e32 v[96:97], v[16:17]
	v_lshl_add_u64 v[98:99], v[96:97], 0, s[8:9]
	v_lshl_add_u64 v[100:101], v[98:99], 0, s[8:9]
	v_lshl_add_u64 v[102:103], v[100:101], 0, s[8:9]
	global_load_dwordx2 v[36:37], v[96:97], off
	global_load_dwordx2 v[38:39], v[98:99], off
	global_load_dwordx2 v[40:41], v[100:101], off
	global_load_dwordx2 v[42:43], v[102:103], off
	s_waitcnt vmcnt(0)
	v_lshlrev_b32_e32 v104, 16, v36
	v_and_b32_e32 v105, 0xffff0000, v36
	v_lshlrev_b32_e32 v106, 16, v37
	v_and_b32_e32 v107, 0xffff0000, v37
	v_lshlrev_b32_e32 v116, 16, v38
	v_and_b32_e32 v117, 0xffff0000, v38
	v_lshlrev_b32_e32 v118, 16, v39
	v_and_b32_e32 v119, 0xffff0000, v39
	v_lshlrev_b32_e32 v128, 16, v40
	v_and_b32_e32 v129, 0xffff0000, v40
	v_lshlrev_b32_e32 v130, 16, v41
	v_and_b32_e32 v131, 0xffff0000, v41
	v_lshlrev_b32_e32 v140, 16, v42
	v_and_b32_e32 v141, 0xffff0000, v42
	v_lshlrev_b32_e32 v142, 16, v43
	v_and_b32_e32 v143, 0xffff0000, v43
	v_mov_b32_e32 v108, v104
	v_mov_b32_e32 v109, v106
	v_mov_b32_e32 v110, v105
	v_mov_b32_e32 v111, v107
	v_mov_b32_e32 v120, v116
	v_mov_b32_e32 v121, v118
	v_mov_b32_e32 v122, v117
	v_mov_b32_e32 v123, v119
	v_mov_b32_e32 v132, v128
	v_mov_b32_e32 v133, v130
	v_mov_b32_e32 v134, v129
	v_mov_b32_e32 v135, v131
	v_mov_b32_e32 v144, v140
	v_mov_b32_e32 v145, v142
	v_mov_b32_e32 v146, v141
	v_mov_b32_e32 v147, v143
	v_pk_mul_f32 v[110:111], v[110:111], v[110:111]
	v_pk_mul_f32 v[122:123], v[122:123], v[122:123]
	v_pk_mul_f32 v[134:135], v[134:135], v[134:135]
	v_pk_mul_f32 v[146:147], v[146:147], v[146:147]
	v_pk_fma_f32 v[108:109], v[108:109], v[108:109], v[110:111]
	v_pk_fma_f32 v[120:121], v[120:121], v[120:121], v[122:123]
	v_pk_fma_f32 v[132:133], v[132:133], v[132:133], v[134:135]
	v_pk_fma_f32 v[144:145], v[144:145], v[144:145], v[146:147]
	v_add_f32_e32 v112, v108, v109
	v_add_f32_e32 v124, v120, v121
	v_add_f32_e32 v136, v132, v133
	v_add_f32_e32 v148, v144, v145
	s_nop 1
	v_add_f32_dpp v112, v112, v112 quad_perm:[1,0,3,2] row_mask:0xf bank_mask:0xf
	v_add_f32_dpp v124, v124, v124 quad_perm:[1,0,3,2] row_mask:0xf bank_mask:0xf
	v_add_f32_dpp v136, v136, v136 quad_perm:[1,0,3,2] row_mask:0xf bank_mask:0xf
	v_add_f32_dpp v148, v148, v148 quad_perm:[1,0,3,2] row_mask:0xf bank_mask:0xf
	s_nop 1
	v_add_f32_dpp v112, v112, v112 quad_perm:[2,3,0,1] row_mask:0xf bank_mask:0xf
	v_add_f32_dpp v124, v124, v124 quad_perm:[2,3,0,1] row_mask:0xf bank_mask:0xf
	v_add_f32_dpp v136, v136, v136 quad_perm:[2,3,0,1] row_mask:0xf bank_mask:0xf
	v_add_f32_dpp v148, v148, v148 quad_perm:[2,3,0,1] row_mask:0xf bank_mask:0xf
	s_nop 1
	v_add_f32_dpp v112, v112, v112 row_half_mirror row_mask:0xf bank_mask:0xf
	v_add_f32_dpp v124, v124, v124 row_half_mirror row_mask:0xf bank_mask:0xf
	v_add_f32_dpp v136, v136, v136 row_half_mirror row_mask:0xf bank_mask:0xf
	v_add_f32_dpp v148, v148, v148 row_half_mirror row_mask:0xf bank_mask:0xf
	s_nop 1
	v_add_f32_dpp v112, v112, v112 row_mirror row_mask:0xf bank_mask:0xf
	v_add_f32_dpp v124, v124, v124 row_mirror row_mask:0xf bank_mask:0xf
	v_add_f32_dpp v136, v136, v136 row_mirror row_mask:0xf bank_mask:0xf
	v_add_f32_dpp v148, v148, v148 row_mirror row_mask:0xf bank_mask:0xf
	v_fmamk_f32 v112, v112, 0x3c800000, v32
	v_fmamk_f32 v124, v124, 0x3c800000, v32
	v_fmamk_f32 v136, v136, 0x3c800000, v32
	v_fmamk_f32 v148, v148, 0x3c800000, v32
	v_rsq_f32_e32 v112, v112
	v_rsq_f32_e32 v124, v124
	v_rsq_f32_e32 v136, v136
	v_rsq_f32_e32 v148, v148
	s_nop 0
	v_pk_mul_f32 v[108:109], v[0:1], v[112:113] op_sel_hi:[1,0]
	v_pk_mul_f32 v[110:111], v[2:3], v[112:113] op_sel_hi:[1,0]
; __device__ __forceinline__ unsigned pk2(float lo, float hi) { f32x2 v = {lo, hi}; bf16x2_t b = __builtin_convertvector(v, bf16x2_t); return __builtin_bit_cast(unsigned, b); }
; __device__ __forceinline__ void kprep_phase(const Args& a) {
;     ...
;         ss += __shfl_xor(ss, 1); ss += __shfl_xor(ss, 2); ss += __shfl_xor(ss, 4); ss += __shfl_xor(ss, 8);
;         const float rstd = rsqrtf(ss * (1.0f / 64.0f) + 1e-6f);
;         f0 *= rstd * g[0]; f1 *= rstd * g[1]; f2 *= rstd * g[2]; f3 *= rstd * g[3];
;         if (row < M_) {
;             const float p0 = __shfl_xor(f0, 8), p1 = __shfl_xor(f1, 8), p2 = __shfl_xor(f2, 8), p3 = __shfl_xor(f3, 8);
;             const float* rp = ROPE + (size_t)(row & (SEQ - 1)) * 64 + j; const f32x4 cs = *(const f32x4*)rp, sn = *(const f32x4*)(rp + 32);
;             if (lowhalf) { f0 = f0 * cs[0] - p0 * sn[0]; f1 = f1 * cs[1] - p1 * sn[1]; f2 = f2 * cs[2] - p2 * sn[2]; f3 = f3 * cs[3] - p3 * sn[3]; }
;             else         { f0 = p0 * sn[0] + f0 * cs[0]; f1 = p1 * sn[1] + f1 * cs[1]; f2 = p2 * sn[2] + f2 * cs[2]; f3 = p3 * sn[3] + f3 * cs[3]; }
;         }
;         u32x2 o; o.x = pk2(f0, f1); o.y = pk2(f2, f3); *p = o;
;     }
	v_pk_mul_f32 v[120:121], v[0:1], v[124:125] op_sel_hi:[1,0]
	v_pk_mul_f32 v[122:123], v[2:3], v[124:125] op_sel_hi:[1,0]
	v_pk_mul_f32 v[132:133], v[0:1], v[136:137] op_sel_hi:[1,0]
	v_pk_mul_f32 v[134:135], v[2:3], v[136:137] op_sel_hi:[1,0]
	v_pk_mul_f32 v[144:145], v[0:1], v[148:149] op_sel_hi:[1,0]
	v_pk_mul_f32 v[146:147], v[2:3], v[148:149] op_sel_hi:[1,0]
	v_pk_mul_f32 v[104:105], v[108:109], v[104:105]
	v_pk_mul_f32 v[106:107], v[110:111], v[106:107]
	v_pk_mul_f32 v[116:117], v[120:121], v[116:117]
	v_pk_mul_f32 v[118:119], v[122:123], v[118:119]
	v_pk_mul_f32 v[128:129], v[132:133], v[128:129]
	v_pk_mul_f32 v[130:131], v[134:135], v[130:131]
	v_pk_mul_f32 v[140:141], v[144:145], v[140:141]
	v_pk_mul_f32 v[142:143], v[146:147], v[142:143]
	s_nop 1
	v_mov_b32_dpp v108, v104 row_ror:8 row_mask:0xf bank_mask:0xf
	v_mov_b32_dpp v109, v105 row_ror:8 row_mask:0xf bank_mask:0xf
	v_mov_b32_dpp v110, v106 row_ror:8 row_mask:0xf bank_mask:0xf
	v_mov_b32_dpp v111, v107 row_ror:8 row_mask:0xf bank_mask:0xf
	v_mov_b32_dpp v120, v116 row_ror:8 row_mask:0xf bank_mask:0xf
	v_mov_b32_dpp v121, v117 row_ror:8 row_mask:0xf bank_mask:0xf
	v_mov_b32_dpp v122, v118 row_ror:8 row_mask:0xf bank_mask:0xf
	v_mov_b32_dpp v123, v119 row_ror:8 row_mask:0xf bank_mask:0xf
	v_mov_b32_dpp v132, v128 row_ror:8 row_mask:0xf bank_mask:0xf
	v_mov_b32_dpp v133, v129 row_ror:8 row_mask:0xf bank_mask:0xf
	v_mov_b32_dpp v134, v130 row_ror:8 row_mask:0xf bank_mask:0xf
	v_mov_b32_dpp v135, v131 row_ror:8 row_mask:0xf bank_mask:0xf
	v_mov_b32_dpp v144, v140 row_ror:8 row_mask:0xf bank_mask:0xf
	v_mov_b32_dpp v145, v141 row_ror:8 row_mask:0xf bank_mask:0xf
	v_mov_b32_dpp v146, v142 row_ror:8 row_mask:0xf bank_mask:0xf
	v_mov_b32_dpp v147, v143 row_ror:8 row_mask:0xf bank_mask:0xf
	v_pk_mul_f32 v[108:109], v[68:69], v[108:109]
	v_pk_mul_f32 v[110:111], v[70:71], v[110:111]
	v_pk_mul_f32 v[120:121], v[76:77], v[120:121]
	v_pk_mul_f32 v[122:123], v[78:79], v[122:123]
	v_pk_mul_f32 v[132:133], v[84:85], v[132:133]
	v_pk_mul_f32 v[134:135], v[86:87], v[134:135]
	v_pk_mul_f32 v[144:145], v[92:93], v[144:145]
	v_pk_mul_f32 v[146:147], v[94:95], v[146:147]
	v_xor_b32_e32 v108, v108, v33
	v_xor_b32_e32 v109, v109, v33
	v_xor_b32_e32 v110, v110, v33
	v_xor_b32_e32 v111, v111, v33
	v_xor_b32_e32 v120, v120, v33
	v_xor_b32_e32 v121, v121, v33
	v_xor_b32_e32 v122, v122, v33
	v_xor_b32_e32 v123, v123, v33
	v_xor_b32_e32 v132, v132, v33
	v_xor_b32_e32 v133, v133, v33
	v_xor_b32_e32 v134, v134, v33
	v_xor_b32_e32 v135, v135, v33
	v_xor_b32_e32 v144, v144, v33
	v_xor_b32_e32 v145, v145, v33
	v_xor_b32_e32 v146, v146, v33
	v_xor_b32_e32 v147, v147, v33
	v_pk_fma_f32 v[104:105], v[104:105], v[64:65], v[108:109]
	v_pk_fma_f32 v[106:107], v[106:107], v[66:67], v[110:111]
	v_pk_fma_f32 v[116:117], v[116:117], v[72:73], v[120:121]
	v_pk_fma_f32 v[118:119], v[118:119], v[74:75], v[122:123]
	v_pk_fma_f32 v[128:129], v[128:129], v[80:81], v[132:133]
	v_pk_fma_f32 v[130:131], v[130:131], v[82:83], v[134:135]
	v_pk_fma_f32 v[140:141], v[140:141], v[88:89], v[144:145]
	v_pk_fma_f32 v[142:143], v[142:143], v[90:91], v[146:147]
	v_cvt_pk_bf16_f32 v36, v104, v105
	v_cvt_pk_bf16_f32 v37, v106, v107
	v_cvt_pk_bf16_f32 v38, v116, v117
	v_cvt_pk_bf16_f32 v39, v118, v119
	v_cvt_pk_bf16_f32 v40, v128, v129
	v_cvt_pk_bf16_f32 v41, v130, v131
	v_cvt_pk_bf16_f32 v42, v140, v141
	v_cvt_pk_bf16_f32 v43, v142, v143
	global_store_dwordx2 v[96:97], v[36:37], off
	global_store_dwordx2 v[98:99], v[38:39], off
	global_store_dwordx2 v[100:101], v[40:41], off
	global_store_dwordx2 v[102:103], v[42:43], off
	v_lshl_add_u64 v[16:17], v[102:103], 0, s[8:9]
	s_add_i32 s0, s0, 1
	s_cmp_lt_u32 s0, 8
	s_cbranch_scc1 .Lkp_loop
	global_load_dwordx2 v[36:37], v[16:17], off
	v_mov_b64_e32 v[96:97], v[16:17]
	s_waitcnt vmcnt(0)
	v_lshlrev_b32_e32 v104, 16, v36
	v_and_b32_e32 v105, 0xffff0000, v36
	v_lshlrev_b32_e32 v106, 16, v37
	v_and_b32_e32 v107, 0xffff0000, v37
	v_mov_b32_e32 v108, v104
	v_mov_b32_e32 v109, v106
	v_mov_b32_e32 v110, v105
	v_mov_b32_e32 v111, v107
	v_pk_mul_f32 v[110:111], v[110:111], v[110:111]
	s_nop 0
	v_pk_fma_f32 v[108:109], v[108:109], v[108:109], v[110:111]
	s_nop 0
	v_add_f32_e32 v112, v108, v109
	s_nop 1
	v_add_f32_dpp v112, v112, v112 quad_perm:[1,0,3,2] row_mask:0xf bank_mask:0xf
	s_nop 1
	v_add_f32_dpp v112, v112, v112 quad_perm:[2,3,0,1] row_mask:0xf bank_mask:0xf
	s_nop 1
	v_add_f32_dpp v112, v112, v112 row_half_mirror row_mask:0xf bank_mask:0xf
	s_nop 1
	v_add_f32_dpp v112, v112, v112 row_mirror row_mask:0xf bank_mask:0xf
	v_fmamk_f32 v112, v112, 0x3c800000, v32
	v_rsq_f32_e32 v112, v112
	s_nop 0
	v_pk_mul_f32 v[108:109], v[0:1], v[112:113] op_sel_hi:[1,0]
	v_pk_mul_f32 v[110:111], v[2:3], v[112:113] op_sel_hi:[1,0]
	v_pk_mul_f32 v[104:105], v[108:109], v[104:105]
	v_pk_mul_f32 v[106:107], v[110:111], v[106:107]
	v_cvt_pk_bf16_f32 v36, v104, v105
	v_cvt_pk_bf16_f32 v37, v106, v107
	global_store_dwordx2 v[96:97], v[36:37], off
	s_branch .LBB0_448
